# plus: write-through (sc1) hidden-activation stores in the main gate-up epilogue
# speedup vs baseline: 1.0219x; 1.0014x over previous
.LBB0_830:
	s_lshl_b32 s4, s30, 8
	v_mov_b32_e32 v66, v162
	v_mov_b32_e32 v67, v163
	s_add_i32 s4, s4, s25
	s_nop 0
	v_add_u32_e32 v158, s4, v66
	s_sub_i32 s4, s30, 32
	s_lshr_b32 s4, s4, 3
	s_mulk_i32 s4, 0x1600
	s_addk_i32 s4, 0x1600
	s_cmp_gt_i32 s30, 31
	s_cselect_b32 s30, s4, 0
	s_lshl_b64 s[4:5], s[30:31], 2
	s_add_u32 s6, s3, s4
	s_addc_u32 s7, s12, s5
	s_lshl_b32 s4, s2, 8
	s_ashr_i32 s5, s4, 31
	s_lshl_b64 s[4:5], s[4:5], 2
	s_add_u32 s4, s6, s4
	s_addc_u32 s5, s7, s5
	v_lshlrev_b32_e32 v156, 3, v67
	s_add_u32 s4, s4, s54
	s_addc_u32 s5, s5, 0
	v_ashrrev_i32_e32 v157, 31, v156
	v_ashrrev_i32_e32 v159, 31, v158
	v_lshl_add_u64 v[70:71], v[156:157], 2, s[4:5]
	v_lshl_add_u64 v[160:161], v[158:159], 2, s[42:43]
	global_load_dwordx4 v[74:77], v[70:71], off offset:16
	global_load_dwordx4 v[78:81], v[70:71], off
	global_load_dwordx4 v[66:69], v[70:71], off offset:528
	s_nop 0
	global_load_dwordx4 v[70:73], v[70:71], off offset:512
	s_lshl_b32 s2, s2, 7
	global_load_dword v157, v[160:161], off
	global_load_dword v179, v[160:161], off offset:64
	global_load_dword v177, v[160:161], off offset:128
	global_load_dword v175, v[160:161], off offset:192
	global_load_dword v173, v[160:161], off offset:512
	global_load_dword v171, v[160:161], off offset:576
	global_load_dword v169, v[160:161], off offset:640
	global_load_dword v167, v[160:161], off offset:704
	s_or_b32 s2, s2, s26
	v_add_u32_e32 v160, s2, v156
	v_ashrrev_i32_e32 v161, 31, v160
	s_movk_i32 s2, 0x1600
	v_add_u32_e32 v178, 16, v158
	v_add_u32_e32 v176, 32, v158
	v_add_u32_e32 v174, 48, v158
	v_add_u32_e32 v172, 0x80, v158
	v_add_u32_e32 v170, 0x90, v158
	v_add_u32_e32 v168, 0xa0, v158
	v_add_u32_e32 v166, 0xb0, v158
	s_waitcnt vmcnt(0)
	v_fmamk_f32 v156, v157, 0x3a800000, v202
	v_cmp_gt_f32_e32 vcc, s68, v156
	v_mul_f32_e32 v157, 0x4b800000, v156
	s_nop 0
	v_cndmask_b32_e32 v156, v156, v157, vcc
	v_rsq_f32_e32 v156, v156
	s_nop 0
	v_mul_f32_e32 v157, 0x45800000, v156
	v_cndmask_b32_e32 v180, v156, v157, vcc
	v_mov_b64_e32 v[156:157], s[40:41]
	v_mad_i64_i32 v[182:183], s[4:5], v158, s2, v[156:157]
	v_lshlrev_b64 v[158:159], 1, v[160:161]
	v_pk_fma_f32 v[142:143], v[142:143], v[180:181], v[78:79] op_sel_hi:[1,0,1]
	v_lshl_add_u64 v[160:161], v[182:183], 0, v[158:159]
	v_pk_fma_f32 v[182:183], v[134:135], v[180:181], v[70:71] op_sel_hi:[1,0,1]
	v_pk_fma_f32 v[134:135], v[132:133], v[180:181], v[68:69] op_sel_hi:[1,0,1]
	v_pk_fma_f32 v[132:133], v[130:131], v[180:181], v[66:67] op_sel_hi:[1,0,1]
	v_mul_f32_e32 v130, 0xbfb8aa3b, v142
	v_mul_f32_e32 v131, 0xbfb8aa3b, v143
	v_exp_f32_e32 v130, v130
	v_exp_f32_e32 v131, v131
	v_pk_fma_f32 v[144:145], v[144:145], v[180:181], v[80:81] op_sel_hi:[1,0,1]
	v_pk_fma_f32 v[136:137], v[136:137], v[180:181], v[72:73] op_sel_hi:[1,0,1]
	v_add_f32_e32 v130, 1.0, v130
	v_add_f32_e32 v131, 1.0, v131
	v_rcp_f32_e32 v130, v130
	v_rcp_f32_e32 v131, v131
	v_pk_fma_f32 v[138:139], v[138:139], v[180:181], v[74:75] op_sel_hi:[1,0,1]
	v_pk_fma_f32 v[140:141], v[140:141], v[180:181], v[76:77] op_sel_hi:[1,0,1]
	v_pk_mul_f32 v[130:131], v[142:143], v[130:131]
	s_nop 0
	v_pk_mul_f32 v[130:131], v[182:183], v[130:131]
	s_nop 0
	v_cvt_pk_bf16_f32 v130, v130, v131
	v_mul_f32_e32 v131, 0xbfb8aa3b, v144
	v_exp_f32_e32 v131, v131
	s_nop 0
	v_add_f32_e32 v131, 1.0, v131
	v_rcp_f32_e32 v142, v131
	v_mul_f32_e32 v131, 0xbfb8aa3b, v145
	v_exp_f32_e32 v131, v131
	s_nop 0
	v_add_f32_e32 v131, 1.0, v131
	v_rcp_f32_e32 v143, v131
	s_nop 0
	v_pk_mul_f32 v[142:143], v[144:145], v[142:143]
	s_nop 0
	v_pk_mul_f32 v[136:137], v[136:137], v[142:143]
	s_nop 0
	v_cvt_pk_bf16_f32 v131, v136, v137
	v_mul_f32_e32 v136, 0xbfb8aa3b, v138
	v_mul_f32_e32 v137, 0xbfb8aa3b, v139
	v_exp_f32_e32 v136, v136
	v_exp_f32_e32 v137, v137
	v_add_f32_e32 v136, 1.0, v136
	v_add_f32_e32 v137, 1.0, v137
	v_rcp_f32_e32 v136, v136
	v_rcp_f32_e32 v137, v137
	s_nop 0
	v_pk_mul_f32 v[136:137], v[138:139], v[136:137]
	s_nop 0
	v_pk_mul_f32 v[132:133], v[132:133], v[136:137]
	s_nop 0
	v_cvt_pk_bf16_f32 v132, v132, v133
	v_mul_f32_e32 v133, 0xbfb8aa3b, v140
	v_exp_f32_e32 v133, v133
	s_nop 0
	v_add_f32_e32 v133, 1.0, v133
	v_rcp_f32_e32 v136, v133
	v_mul_f32_e32 v133, 0xbfb8aa3b, v141
	v_exp_f32_e32 v133, v133
	s_nop 0
	v_add_f32_e32 v133, 1.0, v133
	v_rcp_f32_e32 v137, v133
	s_nop 0
	v_pk_mul_f32 v[136:137], v[140:141], v[136:137]
	s_nop 0
	v_pk_mul_f32 v[134:135], v[134:135], v[136:137]
	s_nop 0
	v_cvt_pk_bf16_f32 v133, v134, v135
	global_store_dwordx4 v[160:161], v[130:133], off sc1
	s_nop 1
	v_fmamk_f32 v130, v179, 0x3a800000, v202
	v_cmp_gt_f32_e32 vcc, s68, v130
	v_mul_f32_e32 v131, 0x4b800000, v130
	v_mad_i64_i32 v[132:133], s[4:5], v178, s2, v[156:157]
	v_cndmask_b32_e32 v130, v130, v131, vcc
	v_rsq_f32_e32 v130, v130
	v_lshl_add_u64 v[132:133], v[132:133], 0, v[158:159]
	v_mul_f32_e32 v131, 0x45800000, v130
	v_cndmask_b32_e32 v130, v130, v131, vcc
	v_pk_fma_f32 v[126:127], v[126:127], v[130:131], v[78:79] op_sel_hi:[1,0,1]
	v_pk_fma_f32 v[134:135], v[116:117], v[130:131], v[68:69] op_sel_hi:[1,0,1]
	v_pk_fma_f32 v[116:117], v[114:115], v[130:131], v[66:67] op_sel_hi:[1,0,1]
	v_mul_f32_e32 v114, 0xbfb8aa3b, v126
	v_mul_f32_e32 v115, 0xbfb8aa3b, v127
	v_exp_f32_e32 v114, v114
	v_exp_f32_e32 v115, v115
	v_pk_fma_f32 v[118:119], v[118:119], v[130:131], v[70:71] op_sel_hi:[1,0,1]
	v_pk_fma_f32 v[128:129], v[128:129], v[130:131], v[80:81] op_sel_hi:[1,0,1]
	v_add_f32_e32 v114, 1.0, v114
	v_add_f32_e32 v115, 1.0, v115
	v_rcp_f32_e32 v114, v114
	v_rcp_f32_e32 v115, v115
	v_pk_fma_f32 v[120:121], v[120:121], v[130:131], v[72:73] op_sel_hi:[1,0,1]
	v_pk_fma_f32 v[122:123], v[122:123], v[130:131], v[74:75] op_sel_hi:[1,0,1]
	v_pk_fma_f32 v[124:125], v[124:125], v[130:131], v[76:77] op_sel_hi:[1,0,1]
	v_pk_mul_f32 v[114:115], v[126:127], v[114:115]
	s_nop 0
	v_pk_mul_f32 v[114:115], v[118:119], v[114:115]
	s_nop 0
	v_cvt_pk_bf16_f32 v114, v114, v115
	v_mul_f32_e32 v115, 0xbfb8aa3b, v128
	v_exp_f32_e32 v115, v115
	s_nop 0
	v_add_f32_e32 v115, 1.0, v115
	v_rcp_f32_e32 v118, v115
	v_mul_f32_e32 v115, 0xbfb8aa3b, v129
	v_exp_f32_e32 v115, v115
	s_nop 0
	v_add_f32_e32 v115, 1.0, v115
	v_rcp_f32_e32 v119, v115
	s_nop 0
	v_pk_mul_f32 v[118:119], v[128:129], v[118:119]
	s_nop 0
	v_pk_mul_f32 v[118:119], v[120:121], v[118:119]
	s_nop 0
	v_cvt_pk_bf16_f32 v115, v118, v119
	v_mul_f32_e32 v118, 0xbfb8aa3b, v122
	v_mul_f32_e32 v119, 0xbfb8aa3b, v123
	v_exp_f32_e32 v118, v118
	v_exp_f32_e32 v119, v119
	v_add_f32_e32 v118, 1.0, v118
	v_add_f32_e32 v119, 1.0, v119
	v_rcp_f32_e32 v118, v118
	v_rcp_f32_e32 v119, v119
	s_nop 0
	v_pk_mul_f32 v[118:119], v[122:123], v[118:119]
	s_nop 0
	v_pk_mul_f32 v[116:117], v[116:117], v[118:119]
	s_nop 0
	v_cvt_pk_bf16_f32 v116, v116, v117
	v_mul_f32_e32 v117, 0xbfb8aa3b, v124
	v_exp_f32_e32 v117, v117
	s_nop 0
	v_add_f32_e32 v117, 1.0, v117
	v_rcp_f32_e32 v118, v117
	v_mul_f32_e32 v117, 0xbfb8aa3b, v125
	v_exp_f32_e32 v117, v117
	s_nop 0
	v_add_f32_e32 v117, 1.0, v117
	v_rcp_f32_e32 v119, v117
	s_nop 0
	v_pk_mul_f32 v[118:119], v[124:125], v[118:119]
	s_nop 0
	v_pk_mul_f32 v[118:119], v[134:135], v[118:119]
	s_nop 0
	v_cvt_pk_bf16_f32 v117, v118, v119
	global_store_dwordx4 v[132:133], v[114:117], off sc1
	s_nop 1
	v_fmamk_f32 v114, v177, 0x3a800000, v202
	v_cmp_gt_f32_e32 vcc, s68, v114
	v_mul_f32_e32 v115, 0x4b800000, v114
	v_mad_i64_i32 v[116:117], s[4:5], v176, s2, v[156:157]
	v_cndmask_b32_e32 v114, v114, v115, vcc
	v_rsq_f32_e32 v114, v114
	v_lshl_add_u64 v[116:117], v[116:117], 0, v[158:159]
	v_mul_f32_e32 v115, 0x45800000, v114
	v_cndmask_b32_e32 v114, v114, v115, vcc
	v_pk_fma_f32 v[110:111], v[110:111], v[114:115], v[78:79] op_sel_hi:[1,0,1]
	v_pk_fma_f32 v[118:119], v[100:101], v[114:115], v[68:69] op_sel_hi:[1,0,1]
	v_pk_fma_f32 v[100:101], v[98:99], v[114:115], v[66:67] op_sel_hi:[1,0,1]
	v_mul_f32_e32 v98, 0xbfb8aa3b, v110
	v_mul_f32_e32 v99, 0xbfb8aa3b, v111
	v_exp_f32_e32 v98, v98
	v_exp_f32_e32 v99, v99
	v_pk_fma_f32 v[102:103], v[102:103], v[114:115], v[70:71] op_sel_hi:[1,0,1]
	v_pk_fma_f32 v[112:113], v[112:113], v[114:115], v[80:81] op_sel_hi:[1,0,1]
	v_add_f32_e32 v98, 1.0, v98
	v_add_f32_e32 v99, 1.0, v99
	v_rcp_f32_e32 v98, v98
	v_rcp_f32_e32 v99, v99
	v_pk_fma_f32 v[104:105], v[104:105], v[114:115], v[72:73] op_sel_hi:[1,0,1]
	v_pk_fma_f32 v[106:107], v[106:107], v[114:115], v[74:75] op_sel_hi:[1,0,1]
	v_pk_fma_f32 v[108:109], v[108:109], v[114:115], v[76:77] op_sel_hi:[1,0,1]
	v_pk_mul_f32 v[98:99], v[110:111], v[98:99]
	s_nop 0
	v_pk_mul_f32 v[98:99], v[102:103], v[98:99]
	s_nop 0
	v_cvt_pk_bf16_f32 v98, v98, v99
	v_mul_f32_e32 v99, 0xbfb8aa3b, v112
	v_exp_f32_e32 v99, v99
	s_nop 0
	v_add_f32_e32 v99, 1.0, v99
	v_rcp_f32_e32 v102, v99
	v_mul_f32_e32 v99, 0xbfb8aa3b, v113
	v_exp_f32_e32 v99, v99
	s_nop 0
	v_add_f32_e32 v99, 1.0, v99
	v_rcp_f32_e32 v103, v99
	s_nop 0
	v_pk_mul_f32 v[102:103], v[112:113], v[102:103]
	s_nop 0
	v_pk_mul_f32 v[102:103], v[104:105], v[102:103]
	s_nop 0
	v_cvt_pk_bf16_f32 v99, v102, v103
	v_mul_f32_e32 v102, 0xbfb8aa3b, v106
	v_mul_f32_e32 v103, 0xbfb8aa3b, v107
	v_exp_f32_e32 v102, v102
	v_exp_f32_e32 v103, v103
	v_add_f32_e32 v102, 1.0, v102
	v_add_f32_e32 v103, 1.0, v103
	v_rcp_f32_e32 v102, v102
	v_rcp_f32_e32 v103, v103
	s_nop 0
	v_pk_mul_f32 v[102:103], v[106:107], v[102:103]
	s_nop 0
	v_pk_mul_f32 v[100:101], v[100:101], v[102:103]
	s_nop 0
	v_cvt_pk_bf16_f32 v100, v100, v101
	v_mul_f32_e32 v101, 0xbfb8aa3b, v108
	v_exp_f32_e32 v101, v101
	s_nop 0
	v_add_f32_e32 v101, 1.0, v101
	v_rcp_f32_e32 v102, v101
	v_mul_f32_e32 v101, 0xbfb8aa3b, v109
	v_exp_f32_e32 v101, v101
	s_nop 0
	v_add_f32_e32 v101, 1.0, v101
	v_rcp_f32_e32 v103, v101
	s_nop 0
	v_pk_mul_f32 v[102:103], v[108:109], v[102:103]
	s_nop 0
	v_pk_mul_f32 v[102:103], v[118:119], v[102:103]
	s_nop 0
	v_cvt_pk_bf16_f32 v101, v102, v103
	global_store_dwordx4 v[116:117], v[98:101], off sc1
	s_nop 1
	v_fmamk_f32 v98, v175, 0x3a800000, v202
	v_cmp_gt_f32_e32 vcc, s68, v98
	v_mul_f32_e32 v99, 0x4b800000, v98
	v_mad_i64_i32 v[100:101], s[4:5], v174, s2, v[156:157]
	v_cndmask_b32_e32 v98, v98, v99, vcc
	v_rsq_f32_e32 v98, v98
	v_lshl_add_u64 v[100:101], v[100:101], 0, v[158:159]
	v_mul_f32_e32 v99, 0x45800000, v98
	v_cndmask_b32_e32 v98, v98, v99, vcc
	v_pk_fma_f32 v[94:95], v[94:95], v[98:99], v[78:79] op_sel_hi:[1,0,1]
	v_pk_fma_f32 v[102:103], v[84:85], v[98:99], v[68:69] op_sel_hi:[1,0,1]
	v_pk_fma_f32 v[84:85], v[82:83], v[98:99], v[66:67] op_sel_hi:[1,0,1]
	v_mul_f32_e32 v82, 0xbfb8aa3b, v94
	v_mul_f32_e32 v83, 0xbfb8aa3b, v95
	v_exp_f32_e32 v82, v82
	v_exp_f32_e32 v83, v83
	v_pk_fma_f32 v[86:87], v[86:87], v[98:99], v[70:71] op_sel_hi:[1,0,1]
	v_pk_fma_f32 v[96:97], v[96:97], v[98:99], v[80:81] op_sel_hi:[1,0,1]
	v_add_f32_e32 v82, 1.0, v82
	v_add_f32_e32 v83, 1.0, v83
	v_rcp_f32_e32 v82, v82
	v_rcp_f32_e32 v83, v83
	v_pk_fma_f32 v[88:89], v[88:89], v[98:99], v[72:73] op_sel_hi:[1,0,1]
	v_pk_fma_f32 v[90:91], v[90:91], v[98:99], v[74:75] op_sel_hi:[1,0,1]
	v_pk_fma_f32 v[92:93], v[92:93], v[98:99], v[76:77] op_sel_hi:[1,0,1]
	v_pk_mul_f32 v[82:83], v[94:95], v[82:83]
	s_nop 0
	v_pk_mul_f32 v[82:83], v[86:87], v[82:83]
	s_nop 0
	v_cvt_pk_bf16_f32 v82, v82, v83
	v_mul_f32_e32 v83, 0xbfb8aa3b, v96
	v_exp_f32_e32 v83, v83
	s_nop 0
	v_add_f32_e32 v83, 1.0, v83
	v_rcp_f32_e32 v86, v83
	v_mul_f32_e32 v83, 0xbfb8aa3b, v97
	v_exp_f32_e32 v83, v83
	s_nop 0
	v_add_f32_e32 v83, 1.0, v83
	v_rcp_f32_e32 v87, v83
	s_nop 0
	v_pk_mul_f32 v[86:87], v[96:97], v[86:87]
	s_nop 0
	v_pk_mul_f32 v[86:87], v[88:89], v[86:87]
	s_nop 0
	v_cvt_pk_bf16_f32 v83, v86, v87
	v_mul_f32_e32 v86, 0xbfb8aa3b, v90
	v_mul_f32_e32 v87, 0xbfb8aa3b, v91
	v_exp_f32_e32 v86, v86
	v_exp_f32_e32 v87, v87
	v_add_f32_e32 v86, 1.0, v86
	v_add_f32_e32 v87, 1.0, v87
	v_rcp_f32_e32 v86, v86
	v_rcp_f32_e32 v87, v87
	s_nop 0
	v_pk_mul_f32 v[86:87], v[90:91], v[86:87]
	s_nop 0
	v_pk_mul_f32 v[84:85], v[84:85], v[86:87]
	s_nop 0
	v_cvt_pk_bf16_f32 v84, v84, v85
	v_mul_f32_e32 v85, 0xbfb8aa3b, v92
	v_exp_f32_e32 v85, v85
	s_nop 0
	v_add_f32_e32 v85, 1.0, v85
	v_rcp_f32_e32 v86, v85
	v_mul_f32_e32 v85, 0xbfb8aa3b, v93
	v_exp_f32_e32 v85, v85
	s_nop 0
	v_add_f32_e32 v85, 1.0, v85
	v_rcp_f32_e32 v87, v85
	s_nop 0
	v_pk_mul_f32 v[86:87], v[92:93], v[86:87]
	s_nop 0
	v_pk_mul_f32 v[86:87], v[102:103], v[86:87]
	s_nop 0
	v_cvt_pk_bf16_f32 v85, v86, v87
	global_store_dwordx4 v[100:101], v[82:85], off sc1
	s_nop 1
	v_fmamk_f32 v82, v173, 0x3a800000, v202
	v_cmp_gt_f32_e32 vcc, s68, v82
	v_mul_f32_e32 v83, 0x4b800000, v82
	v_mad_i64_i32 v[84:85], s[4:5], v172, s2, v[156:157]
	v_cndmask_b32_e32 v82, v82, v83, vcc
	v_rsq_f32_e32 v82, v82
	v_lshl_add_u64 v[84:85], v[84:85], 0, v[158:159]
	v_mul_f32_e32 v83, 0x45800000, v82
	v_cndmask_b32_e32 v82, v82, v83, vcc
	v_pk_fma_f32 v[62:63], v[62:63], v[82:83], v[78:79] op_sel_hi:[1,0,1]
	v_pk_fma_f32 v[86:87], v[52:53], v[82:83], v[68:69] op_sel_hi:[1,0,1]
	v_pk_fma_f32 v[52:53], v[50:51], v[82:83], v[66:67] op_sel_hi:[1,0,1]
	v_mul_f32_e32 v50, 0xbfb8aa3b, v62
	v_mul_f32_e32 v51, 0xbfb8aa3b, v63
	v_exp_f32_e32 v50, v50
	v_exp_f32_e32 v51, v51
	v_pk_fma_f32 v[54:55], v[54:55], v[82:83], v[70:71] op_sel_hi:[1,0,1]
	v_pk_fma_f32 v[64:65], v[64:65], v[82:83], v[80:81] op_sel_hi:[1,0,1]
	v_add_f32_e32 v50, 1.0, v50
	v_add_f32_e32 v51, 1.0, v51
	v_rcp_f32_e32 v50, v50
	v_rcp_f32_e32 v51, v51
	v_pk_fma_f32 v[56:57], v[56:57], v[82:83], v[72:73] op_sel_hi:[1,0,1]
	v_pk_fma_f32 v[58:59], v[58:59], v[82:83], v[74:75] op_sel_hi:[1,0,1]
	v_pk_fma_f32 v[60:61], v[60:61], v[82:83], v[76:77] op_sel_hi:[1,0,1]
	v_pk_mul_f32 v[50:51], v[62:63], v[50:51]
	s_nop 0
	v_pk_mul_f32 v[50:51], v[54:55], v[50:51]
	s_nop 0
	v_cvt_pk_bf16_f32 v50, v50, v51
	v_mul_f32_e32 v51, 0xbfb8aa3b, v64
	v_exp_f32_e32 v51, v51
	s_nop 0
	v_add_f32_e32 v51, 1.0, v51
	v_rcp_f32_e32 v54, v51
	v_mul_f32_e32 v51, 0xbfb8aa3b, v65
	v_exp_f32_e32 v51, v51
	s_nop 0
	v_add_f32_e32 v51, 1.0, v51
	v_rcp_f32_e32 v55, v51
	s_nop 0
	v_pk_mul_f32 v[54:55], v[64:65], v[54:55]
	s_nop 0
	v_pk_mul_f32 v[54:55], v[56:57], v[54:55]
	s_nop 0
	v_cvt_pk_bf16_f32 v51, v54, v55
	v_mul_f32_e32 v54, 0xbfb8aa3b, v58
	v_mul_f32_e32 v55, 0xbfb8aa3b, v59
	v_exp_f32_e32 v54, v54
	v_exp_f32_e32 v55, v55
	v_add_f32_e32 v54, 1.0, v54
	v_add_f32_e32 v55, 1.0, v55
	v_rcp_f32_e32 v54, v54
	v_rcp_f32_e32 v55, v55
	s_nop 0
	v_pk_mul_f32 v[54:55], v[58:59], v[54:55]
	s_nop 0
	v_pk_mul_f32 v[52:53], v[52:53], v[54:55]
	s_nop 0
	v_cvt_pk_bf16_f32 v52, v52, v53
	v_mul_f32_e32 v53, 0xbfb8aa3b, v60
	v_exp_f32_e32 v53, v53
	s_nop 0
	v_add_f32_e32 v53, 1.0, v53
	v_rcp_f32_e32 v54, v53
	v_mul_f32_e32 v53, 0xbfb8aa3b, v61
	v_exp_f32_e32 v53, v53
	s_nop 0
	v_add_f32_e32 v53, 1.0, v53
	v_rcp_f32_e32 v55, v53
	s_nop 0
	v_pk_mul_f32 v[54:55], v[60:61], v[54:55]
	s_nop 0
	v_pk_mul_f32 v[54:55], v[86:87], v[54:55]
	s_nop 0
	v_cvt_pk_bf16_f32 v53, v54, v55
	global_store_dwordx4 v[84:85], v[50:53], off sc1
	s_nop 1
	v_fmamk_f32 v50, v171, 0x3a800000, v202
	v_cmp_gt_f32_e32 vcc, s68, v50
	v_mul_f32_e32 v51, 0x4b800000, v50
	v_mad_i64_i32 v[52:53], s[4:5], v170, s2, v[156:157]
	v_cndmask_b32_e32 v50, v50, v51, vcc
	v_rsq_f32_e32 v50, v50
	v_lshl_add_u64 v[52:53], v[52:53], 0, v[158:159]
	v_mul_f32_e32 v51, 0x45800000, v50
	v_cndmask_b32_e32 v50, v50, v51, vcc
	v_pk_fma_f32 v[46:47], v[46:47], v[50:51], v[78:79] op_sel_hi:[1,0,1]
	v_pk_fma_f32 v[54:55], v[36:37], v[50:51], v[68:69] op_sel_hi:[1,0,1]
	v_pk_fma_f32 v[36:37], v[34:35], v[50:51], v[66:67] op_sel_hi:[1,0,1]
	v_mul_f32_e32 v34, 0xbfb8aa3b, v46
	v_mul_f32_e32 v35, 0xbfb8aa3b, v47
	v_exp_f32_e32 v34, v34
	v_exp_f32_e32 v35, v35
	v_pk_fma_f32 v[38:39], v[38:39], v[50:51], v[70:71] op_sel_hi:[1,0,1]
	v_pk_fma_f32 v[48:49], v[48:49], v[50:51], v[80:81] op_sel_hi:[1,0,1]
	v_add_f32_e32 v34, 1.0, v34
	v_add_f32_e32 v35, 1.0, v35
	v_rcp_f32_e32 v34, v34
	v_rcp_f32_e32 v35, v35
	v_pk_fma_f32 v[40:41], v[40:41], v[50:51], v[72:73] op_sel_hi:[1,0,1]
	v_pk_fma_f32 v[42:43], v[42:43], v[50:51], v[74:75] op_sel_hi:[1,0,1]
	v_pk_fma_f32 v[44:45], v[44:45], v[50:51], v[76:77] op_sel_hi:[1,0,1]
	v_pk_mul_f32 v[34:35], v[46:47], v[34:35]
	s_nop 0
	v_pk_mul_f32 v[34:35], v[38:39], v[34:35]
	s_nop 0
	v_cvt_pk_bf16_f32 v34, v34, v35
	v_mul_f32_e32 v35, 0xbfb8aa3b, v48
	v_exp_f32_e32 v35, v35
	s_nop 0
	v_add_f32_e32 v35, 1.0, v35
	v_rcp_f32_e32 v38, v35
	v_mul_f32_e32 v35, 0xbfb8aa3b, v49
	v_exp_f32_e32 v35, v35
	s_nop 0
	v_add_f32_e32 v35, 1.0, v35
	v_rcp_f32_e32 v39, v35
	s_nop 0
	v_pk_mul_f32 v[38:39], v[48:49], v[38:39]
	s_nop 0
	v_pk_mul_f32 v[38:39], v[40:41], v[38:39]
	s_nop 0
	v_cvt_pk_bf16_f32 v35, v38, v39
	v_mul_f32_e32 v38, 0xbfb8aa3b, v42
	v_mul_f32_e32 v39, 0xbfb8aa3b, v43
	v_exp_f32_e32 v38, v38
	v_exp_f32_e32 v39, v39
	v_add_f32_e32 v38, 1.0, v38
	v_add_f32_e32 v39, 1.0, v39
	v_rcp_f32_e32 v38, v38
	v_rcp_f32_e32 v39, v39
	s_nop 0
	v_pk_mul_f32 v[38:39], v[42:43], v[38:39]
	s_nop 0
	v_pk_mul_f32 v[36:37], v[36:37], v[38:39]
	s_nop 0
	v_cvt_pk_bf16_f32 v36, v36, v37
	v_mul_f32_e32 v37, 0xbfb8aa3b, v44
	v_exp_f32_e32 v37, v37
	s_nop 0
	v_add_f32_e32 v37, 1.0, v37
	v_rcp_f32_e32 v38, v37
	v_mul_f32_e32 v37, 0xbfb8aa3b, v45
	v_exp_f32_e32 v37, v37
	s_nop 0
	v_add_f32_e32 v37, 1.0, v37
	v_rcp_f32_e32 v39, v37
	s_nop 0
	v_pk_mul_f32 v[38:39], v[44:45], v[38:39]
	s_nop 0
	v_pk_mul_f32 v[38:39], v[54:55], v[38:39]
	s_nop 0
	v_cvt_pk_bf16_f32 v37, v38, v39
	global_store_dwordx4 v[52:53], v[34:37], off sc1
	s_nop 1
	v_fmamk_f32 v34, v169, 0x3a800000, v202
	v_cmp_gt_f32_e32 vcc, s68, v34
	v_mul_f32_e32 v35, 0x4b800000, v34
	v_mad_i64_i32 v[36:37], s[4:5], v168, s2, v[156:157]
	v_cndmask_b32_e32 v34, v34, v35, vcc
	v_rsq_f32_e32 v34, v34
	v_lshl_add_u64 v[36:37], v[36:37], 0, v[158:159]
	v_mul_f32_e32 v35, 0x45800000, v34
	v_cndmask_b32_e32 v34, v34, v35, vcc
	v_pk_fma_f32 v[30:31], v[30:31], v[34:35], v[78:79] op_sel_hi:[1,0,1]
	v_pk_fma_f32 v[38:39], v[20:21], v[34:35], v[68:69] op_sel_hi:[1,0,1]
	v_pk_fma_f32 v[20:21], v[18:19], v[34:35], v[66:67] op_sel_hi:[1,0,1]
	v_mul_f32_e32 v18, 0xbfb8aa3b, v30
	v_mul_f32_e32 v19, 0xbfb8aa3b, v31
	v_exp_f32_e32 v18, v18
	v_exp_f32_e32 v19, v19
	v_pk_fma_f32 v[22:23], v[22:23], v[34:35], v[70:71] op_sel_hi:[1,0,1]
	v_pk_fma_f32 v[32:33], v[32:33], v[34:35], v[80:81] op_sel_hi:[1,0,1]
	v_add_f32_e32 v18, 1.0, v18
	v_add_f32_e32 v19, 1.0, v19
	v_rcp_f32_e32 v18, v18
	v_rcp_f32_e32 v19, v19
	v_pk_fma_f32 v[24:25], v[24:25], v[34:35], v[72:73] op_sel_hi:[1,0,1]
	v_pk_fma_f32 v[26:27], v[26:27], v[34:35], v[74:75] op_sel_hi:[1,0,1]
	v_pk_fma_f32 v[28:29], v[28:29], v[34:35], v[76:77] op_sel_hi:[1,0,1]
	v_pk_mul_f32 v[18:19], v[30:31], v[18:19]
	s_nop 0
	v_pk_mul_f32 v[18:19], v[22:23], v[18:19]
	s_nop 0
	v_cvt_pk_bf16_f32 v18, v18, v19
	v_mul_f32_e32 v19, 0xbfb8aa3b, v32
	v_exp_f32_e32 v19, v19
	s_nop 0
	v_add_f32_e32 v19, 1.0, v19
	v_rcp_f32_e32 v22, v19
	v_mul_f32_e32 v19, 0xbfb8aa3b, v33
	v_exp_f32_e32 v19, v19
	s_nop 0
	v_add_f32_e32 v19, 1.0, v19
	v_rcp_f32_e32 v23, v19
	s_nop 0
	v_pk_mul_f32 v[22:23], v[32:33], v[22:23]
	s_nop 0
	v_pk_mul_f32 v[22:23], v[24:25], v[22:23]
	s_nop 0
	v_cvt_pk_bf16_f32 v19, v22, v23
	v_mul_f32_e32 v22, 0xbfb8aa3b, v26
	v_mul_f32_e32 v23, 0xbfb8aa3b, v27
	v_exp_f32_e32 v22, v22
	v_exp_f32_e32 v23, v23
	v_add_f32_e32 v22, 1.0, v22
	v_add_f32_e32 v23, 1.0, v23
	v_rcp_f32_e32 v22, v22
	v_rcp_f32_e32 v23, v23
	s_nop 0
	v_pk_mul_f32 v[22:23], v[26:27], v[22:23]
	s_nop 0
	v_pk_mul_f32 v[20:21], v[20:21], v[22:23]
	s_nop 0
	v_cvt_pk_bf16_f32 v20, v20, v21
	v_mul_f32_e32 v21, 0xbfb8aa3b, v28
	v_exp_f32_e32 v21, v21
	s_nop 0
	v_add_f32_e32 v21, 1.0, v21
	v_rcp_f32_e32 v22, v21
	v_mul_f32_e32 v21, 0xbfb8aa3b, v29
	v_exp_f32_e32 v21, v21
	s_nop 0
	v_add_f32_e32 v21, 1.0, v21
	v_rcp_f32_e32 v23, v21
	s_nop 0
	v_pk_mul_f32 v[22:23], v[28:29], v[22:23]
	s_nop 0
	v_pk_mul_f32 v[22:23], v[38:39], v[22:23]
	s_nop 0
	v_cvt_pk_bf16_f32 v21, v22, v23
	global_store_dwordx4 v[36:37], v[18:21], off sc1
	s_nop 1
	v_fmamk_f32 v18, v167, 0x3a800000, v202
	v_cmp_gt_f32_e32 vcc, s68, v18
	v_mul_f32_e32 v19, 0x4b800000, v18
	v_mad_i64_i32 v[20:21], s[4:5], v166, s2, v[156:157]
	v_cndmask_b32_e32 v18, v18, v19, vcc
	v_rsq_f32_e32 v18, v18
	v_lshl_add_u64 v[20:21], v[20:21], 0, v[158:159]
	v_mul_f32_e32 v19, 0x45800000, v18
	v_cndmask_b32_e32 v18, v18, v19, vcc
	v_pk_fma_f32 v[14:15], v[14:15], v[18:19], v[78:79] op_sel_hi:[1,0,1]
	v_pk_fma_f32 v[22:23], v[4:5], v[18:19], v[68:69] op_sel_hi:[1,0,1]
	v_pk_fma_f32 v[4:5], v[2:3], v[18:19], v[66:67] op_sel_hi:[1,0,1]
	v_mul_f32_e32 v2, 0xbfb8aa3b, v14
	v_mul_f32_e32 v3, 0xbfb8aa3b, v15
	v_exp_f32_e32 v2, v2
	v_exp_f32_e32 v3, v3
	v_pk_fma_f32 v[6:7], v[6:7], v[18:19], v[70:71] op_sel_hi:[1,0,1]
	v_pk_fma_f32 v[16:17], v[16:17], v[18:19], v[80:81] op_sel_hi:[1,0,1]
	v_add_f32_e32 v2, 1.0, v2
	v_add_f32_e32 v3, 1.0, v3
	v_rcp_f32_e32 v2, v2
	v_rcp_f32_e32 v3, v3
	v_pk_fma_f32 v[8:9], v[8:9], v[18:19], v[72:73] op_sel_hi:[1,0,1]
	v_pk_fma_f32 v[10:11], v[10:11], v[18:19], v[74:75] op_sel_hi:[1,0,1]
	v_pk_fma_f32 v[12:13], v[12:13], v[18:19], v[76:77] op_sel_hi:[1,0,1]
	v_pk_mul_f32 v[2:3], v[14:15], v[2:3]
	s_nop 0
	v_pk_mul_f32 v[2:3], v[6:7], v[2:3]
	s_nop 0
	v_cvt_pk_bf16_f32 v2, v2, v3
	v_mul_f32_e32 v3, 0xbfb8aa3b, v16
	v_exp_f32_e32 v3, v3
	s_nop 0
	v_add_f32_e32 v3, 1.0, v3
	v_rcp_f32_e32 v6, v3
	v_mul_f32_e32 v3, 0xbfb8aa3b, v17
	v_exp_f32_e32 v3, v3
	s_nop 0
	v_add_f32_e32 v3, 1.0, v3
	v_rcp_f32_e32 v7, v3
	s_nop 0
	v_pk_mul_f32 v[6:7], v[16:17], v[6:7]
	s_nop 0
	v_pk_mul_f32 v[6:7], v[8:9], v[6:7]
	s_nop 0
	v_cvt_pk_bf16_f32 v3, v6, v7
	v_mul_f32_e32 v6, 0xbfb8aa3b, v10
	v_mul_f32_e32 v7, 0xbfb8aa3b, v11
	v_exp_f32_e32 v6, v6
	v_exp_f32_e32 v7, v7
	v_add_f32_e32 v6, 1.0, v6
	v_add_f32_e32 v7, 1.0, v7
	v_rcp_f32_e32 v6, v6
	v_rcp_f32_e32 v7, v7
	s_nop 0
	v_pk_mul_f32 v[6:7], v[10:11], v[6:7]
	s_nop 0
	v_pk_mul_f32 v[4:5], v[4:5], v[6:7]
	s_nop 0
	v_cvt_pk_bf16_f32 v4, v4, v5
	v_mul_f32_e32 v5, 0xbfb8aa3b, v12
	v_exp_f32_e32 v5, v5
	s_nop 0
	v_add_f32_e32 v5, 1.0, v5
	v_rcp_f32_e32 v6, v5
	v_mul_f32_e32 v5, 0xbfb8aa3b, v13
	v_exp_f32_e32 v5, v5
	s_nop 0
	v_add_f32_e32 v5, 1.0, v5
	v_rcp_f32_e32 v7, v5
	s_nop 0
	v_pk_mul_f32 v[6:7], v[12:13], v[6:7]
	s_nop 0
	v_pk_mul_f32 v[6:7], v[22:23], v[6:7]
	s_nop 0
	v_cvt_pk_bf16_f32 v5, v6, v7
	global_store_dwordx4 v[20:21], v[2:5], off sc1
	s_andn2_b64 vcc, exec, s[34:35]
	s_mov_b64 s[4:5], -1
	s_cbranch_vccnz .LBB0_821
	s_andn2_b64 vcc, exec, s[38:39]
	s_cbranch_vccnz .LBB0_820
	s_barrier
	s_branch .LBB0_820
